# plus MLA LDS-DMA K/V staging, DMA issue moved into the post-QK wait-state slot, dead negm copies removed from the GQA loop, final grid barrier skipped
# speedup vs baseline: 1.0892x; 1.0259x over previous
.LBB0_119:
	s_mov_b32 s38, s10
	s_ashr_i32 s9, s8, 31
	s_lshl_b32 s11, s20, 9
	s_add_u32 s12, s14, s11
	s_addc_u32 s13, s15, 0
	s_ashr_i32 s11, s10, 31
	v_lshl_add_u64 v[2:3], s[10:11], 0, v[170:171]
	v_lshl_add_u64 v[6:7], v[174:175], 0, s[10:11]
	v_lshlrev_b64 v[22:23], 12, v[2:3]
	v_lshlrev_b64 v[6:7], 12, v[6:7]
	v_lshl_add_u64 v[10:11], s[10:11], 0, v[172:173]
	v_lshl_add_u64 v[2:3], s[12:13], 0, v[22:23]
	v_mov_b32_e32 v189, v1
	v_lshl_add_u64 v[6:7], s[12:13], 0, v[6:7]
	v_lshlrev_b64 v[24:25], 12, v[10:11]
	v_lshl_add_u64 v[14:15], v[2:3], 0, v[188:189]
	v_lshl_add_u64 v[18:19], v[6:7], 0, v[188:189]
	v_lshl_add_u64 v[10:11], v[176:177], 0, v[24:25]
	global_load_dwordx4 v[2:5], v[14:15], off
	global_load_dwordx4 v[6:9], v[18:19], off
	s_nop 0
	global_load_dwordx4 v[10:13], v[10:11], off
	s_nop 0
	global_load_dwordx4 v[14:17], v[14:15], off offset:256
	s_nop 0
	global_load_dwordx4 v[18:21], v[18:19], off offset:256
	v_add_u32_e32 v26, 16, v198
	s_waitcnt vmcnt(0)
	s_and_b32 s22, s18, 7
	v_lshl_or_b32 v22, s22, 9, v22
	s_lshl_b32 s10, s21, 18
	v_lshl_add_u64 v[192:193], v[184:185], 0, v[24:25]
	v_lshl_add_u64 v[194:195], v[186:187], 0, v[22:23]
	s_add_u32 s21, s10, 0x40000
	s_mov_b32 s22, 0
	v_mov_b32_e32 v234, 0
	v_mov_b32_e32 v189, 0xf149f2ca
	s_mov_b64 s[10:11], 0
	s_waitcnt vmcnt(0)
	ds_write_b128 v26, v[14:17]
	v_add_u32_e32 v14, 16, v199
	s_waitcnt vmcnt(0)
	ds_write_b128 v14, v[18:21]
	v_add_u32_e32 v14, 16, v200
	ds_write_b128 v14, v[2:5] offset:32768
	ds_write_b128 v14, v[6:9] offset:45056
	v_add_u32_e32 v2, 16, v201
	v_mov_b32_e32 v16, v1
	v_mov_b32_e32 v17, v1
	ds_write_b128 v2, v[10:13] offset:32768
	v_mov_b32_e32 v2, v1
	v_mov_b32_e32 v3, v1
	v_mov_b32_e32 v4, v1
	v_mov_b32_e32 v5, v1
	v_mov_b32_e32 v6, v1
	v_mov_b32_e32 v7, v1
	v_mov_b32_e32 v8, v1
	v_mov_b32_e32 v9, v1
	v_mov_b32_e32 v10, v1
	v_mov_b32_e32 v11, v1
	v_mov_b32_e32 v12, v1
	v_mov_b32_e32 v13, v1
	v_mov_b32_e32 v14, v1
	v_mov_b32_e32 v15, v1
	v_mov_b64_e32 v[32:33], v[16:17]
	v_mov_b64_e32 v[48:49], v[16:17]
	v_mov_b64_e32 v[64:65], v[16:17]
	v_mov_b64_e32 v[30:31], v[14:15]
	v_mov_b64_e32 v[28:29], v[12:13]
	v_mov_b64_e32 v[26:27], v[10:11]
	v_mov_b64_e32 v[24:25], v[8:9]
	v_mov_b64_e32 v[22:23], v[6:7]
	v_mov_b64_e32 v[20:21], v[4:5]
	v_mov_b64_e32 v[18:19], v[2:3]
	v_mov_b64_e32 v[46:47], v[14:15]
	v_mov_b64_e32 v[44:45], v[12:13]
	v_mov_b64_e32 v[42:43], v[10:11]
	v_mov_b64_e32 v[40:41], v[8:9]
	v_mov_b64_e32 v[38:39], v[6:7]
	v_mov_b64_e32 v[36:37], v[4:5]
	v_mov_b64_e32 v[34:35], v[2:3]
	v_mov_b64_e32 v[62:63], v[14:15]
	v_mov_b64_e32 v[60:61], v[12:13]
	v_mov_b64_e32 v[58:59], v[10:11]
	v_mov_b64_e32 v[56:57], v[8:9]
	v_mov_b64_e32 v[54:55], v[6:7]
	v_mov_b64_e32 v[52:53], v[4:5]
	v_mov_b64_e32 v[50:51], v[2:3]
	s_waitcnt lgkmcnt(0)
	s_barrier
	s_lshl_b32 s12, s20, 9
	s_add_i32 s12, s12, 0x8400000
	v_and_b32_e32 v66, 63, v178
	v_lshrrev_b32_e32 v67, 6, v178
	v_mul_u32_u24_e32 v68, 0xc0, v67
	v_add_u32_e32 v68, v68, v66
	v_mul_u32_u24_e32 v70, 0xaab, v68
	v_lshrrev_b32_e32 v70, 16, v70
	v_mul_u32_u24_e32 v71, 24, v70
	v_sub_u32_e32 v71, v68, v71
	v_and_b32_e32 v72, 15, v70
	v_xor_b32_e32 v72, v71, v72
	v_lshlrev_b32_e32 v72, 4, v72
	v_add_u32_e32 v72, s12, v72
	v_add_u32_e32 v73, -16, v71
	v_and_b32_e32 v74, 7, v70
	v_xor_b32_e32 v73, v73, v74
	v_lshlrev_b32_e32 v73, 4, v73
	v_add_u32_e32 v73, 0x600, v73
	v_cmp_gt_u32_e32 vcc, 16, v71
	s_nop 1
	v_cndmask_b32_e32 v72, v73, v72, vcc
	v_lshl_add_u32 v146, v70, 12, v72
	v_add_u32_e32 v68, 64, v68
	v_mul_u32_u24_e32 v70, 0xaab, v68
	v_lshrrev_b32_e32 v70, 16, v70
	v_mul_u32_u24_e32 v71, 24, v70
	v_sub_u32_e32 v71, v68, v71
	v_and_b32_e32 v72, 15, v70
	v_xor_b32_e32 v72, v71, v72
	v_lshlrev_b32_e32 v72, 4, v72
	v_add_u32_e32 v72, s12, v72
	v_add_u32_e32 v73, -16, v71
	v_and_b32_e32 v74, 7, v70
	v_xor_b32_e32 v73, v73, v74
	v_lshlrev_b32_e32 v73, 4, v73
	v_add_u32_e32 v73, 0x600, v73
	v_cmp_gt_u32_e32 vcc, 16, v71
	s_nop 1
	v_cndmask_b32_e32 v72, v73, v72, vcc
	v_lshl_add_u32 v147, v70, 12, v72
	v_add_u32_e32 v68, 64, v68
	v_mul_u32_u24_e32 v70, 0xaab, v68
	v_lshrrev_b32_e32 v70, 16, v70
	v_mul_u32_u24_e32 v71, 24, v70
	v_sub_u32_e32 v71, v68, v71
	v_and_b32_e32 v72, 15, v70
	v_xor_b32_e32 v72, v71, v72
	v_lshlrev_b32_e32 v72, 4, v72
	v_add_u32_e32 v72, s12, v72
	v_add_u32_e32 v73, -16, v71
	v_and_b32_e32 v74, 7, v70
	v_xor_b32_e32 v73, v73, v74
	v_lshlrev_b32_e32 v73, 4, v73
	v_add_u32_e32 v73, 0x600, v73
	v_cmp_gt_u32_e32 vcc, 16, v71
	s_nop 1
	v_cndmask_b32_e32 v72, v73, v72, vcc
	v_lshl_add_u32 v148, v70, 12, v72
	v_and_b32_e32 v70, 31, v66
	v_lshrrev_b32_e32 v70, 2, v70
	v_lshl_add_u32 v70, v67, 3, v70
	v_lshrrev_b32_e32 v71, 5, v66
	v_lshlrev_b32_e32 v71, 6, v71
	v_and_b32_e32 v72, 3, v66
	v_lshlrev_b32_e32 v72, 4, v72
	v_add3_u32 v71, v71, v72, s12
	v_add_u32_e32 v71, 0x100, v71
	v_lshl_add_u32 v149, v70, 12, v71
	v_add_u32_e32 v150, 0x80, v149
	s_add_i32 s24, s38, 64
	s_lshl_b32 s24, s24, 12
	s_add_u32 s24, s24, 0x4600000
	s_add_u32 s24, s98, s24
	s_addc_u32 s25, s99, 0
	v_readlane_b32 s26, v254, 10
	s_nop 3
	s_lshr_b32 s36, s26, 6
	s_lshl_b32 s26, s26, 5
	s_add_i32 s26, s26, 0x4010
	s_mul_i32 s36, s36, 0xc00
	s_add_i32 s36, s36, 0x8010
	s_movk_i32 s37, 0x6000
.LBB0_120:
	s_and_b32 s23, s22, 1
	s_mul_i32 s12, s23, 0x6000
	v_add_u32_e32 v191, s12, v203
	v_add_u32_e32 v70, v191, v220
	ds_read_b128 v[66:69], v70 offset:32768
	ds_read_b128 v[70:73], v70 offset:45056
	v_add_u32_e32 v235, v191, v221
	ds_read_b128 v[236:239], v235 offset:32768
	ds_read_b128 v[240:243], v235 offset:45056
	v_add_u32_e32 v235, v191, v222
	s_waitcnt lgkmcnt(3)
	v_mfma_f32_32x32x16_bf16 v[82:97], v[66:69], v[134:137], 0
	s_waitcnt lgkmcnt(2)
	v_mfma_f32_32x32x16_bf16 v[66:81], v[70:73], v[134:137], 0
	s_waitcnt lgkmcnt(1)
	v_mfma_f32_32x32x16_bf16 v[82:97], v[236:239], v[130:133], v[82:97]
	s_waitcnt lgkmcnt(0)
	v_mfma_f32_32x32x16_bf16 v[66:81], v[240:243], v[130:133], v[66:81]
	ds_read_b128 v[236:239], v235 offset:32768
	ds_read_b128 v[240:243], v235 offset:45056
	v_add_u32_e32 v235, v191, v223
	s_waitcnt lgkmcnt(1)
	v_mfma_f32_32x32x16_bf16 v[82:97], v[236:239], v[126:129], v[82:97]
	s_waitcnt lgkmcnt(0)
	v_mfma_f32_32x32x16_bf16 v[66:81], v[240:243], v[126:129], v[66:81]
	ds_read_b128 v[236:239], v235 offset:32768
	ds_read_b128 v[240:243], v235 offset:45056
	v_add_u32_e32 v235, v191, v224
	s_waitcnt lgkmcnt(1)
	v_mfma_f32_32x32x16_bf16 v[82:97], v[236:239], v[122:125], v[82:97]
	s_waitcnt lgkmcnt(0)
	v_mfma_f32_32x32x16_bf16 v[66:81], v[240:243], v[122:125], v[66:81]
	ds_read_b128 v[236:239], v235 offset:32768
	ds_read_b128 v[240:243], v235 offset:45056
	v_add_u32_e32 v235, v191, v225
	s_waitcnt lgkmcnt(1)
	v_mfma_f32_32x32x16_bf16 v[82:97], v[236:239], v[118:121], v[82:97]
	s_waitcnt lgkmcnt(0)
	v_mfma_f32_32x32x16_bf16 v[66:81], v[240:243], v[118:121], v[66:81]
	ds_read_b128 v[236:239], v235 offset:32768
	ds_read_b128 v[240:243], v235 offset:45056
	v_add_u32_e32 v235, v191, v226
	s_waitcnt lgkmcnt(1)
	v_mfma_f32_32x32x16_bf16 v[82:97], v[236:239], v[114:117], v[82:97]
	s_waitcnt lgkmcnt(0)
	v_mfma_f32_32x32x16_bf16 v[66:81], v[240:243], v[114:117], v[66:81]
	ds_read_b128 v[236:239], v235 offset:32768
	ds_read_b128 v[240:243], v235 offset:45056
	v_add_u32_e32 v235, v191, v227
	s_waitcnt lgkmcnt(1)
	v_mfma_f32_32x32x16_bf16 v[82:97], v[236:239], v[110:113], v[82:97]
	s_waitcnt lgkmcnt(0)
	v_mfma_f32_32x32x16_bf16 v[66:81], v[240:243], v[110:113], v[66:81]
	ds_read_b128 v[236:239], v235 offset:32768
	ds_read_b128 v[240:243], v235 offset:45056
	v_add_u32_e32 v235, v191, v228
	s_waitcnt lgkmcnt(1)
	v_mfma_f32_32x32x16_bf16 v[82:97], v[236:239], v[106:109], v[82:97]
	s_waitcnt lgkmcnt(0)
	v_mfma_f32_32x32x16_bf16 v[66:81], v[240:243], v[106:109], v[66:81]
	ds_read_b128 v[236:239], v235 offset:32768
	ds_read_b128 v[240:243], v235 offset:45056
	v_add_u32_e32 v235, v191, v229
	s_waitcnt lgkmcnt(1)
	v_mfma_f32_32x32x16_bf16 v[82:97], v[236:239], v[102:105], v[82:97]
	s_waitcnt lgkmcnt(0)
	v_mfma_f32_32x32x16_bf16 v[66:81], v[240:243], v[102:105], v[66:81]
	ds_read_b128 v[236:239], v235 offset:32768
	ds_read_b128 v[240:243], v235 offset:45056
	v_add_u32_e32 v235, v191, v230
	v_add_u32_e32 v191, v191, v231
	s_waitcnt lgkmcnt(1)
	v_mfma_f32_32x32x16_bf16 v[82:97], v[236:239], v[98:101], v[82:97]
	s_waitcnt lgkmcnt(0)
	v_mfma_f32_32x32x16_bf16 v[66:81], v[240:243], v[98:101], v[66:81]
	ds_read_b128 v[236:239], v235 offset:32768
	ds_read_b128 v[240:243], v235 offset:45056
	s_waitcnt lgkmcnt(1)
	v_mfma_f32_32x32x16_bf16 v[82:97], v[236:239], v[138:141], v[82:97]
	s_waitcnt lgkmcnt(0)
	v_mfma_f32_32x32x16_bf16 v[66:81], v[240:243], v[138:141], v[66:81]
	ds_read_b128 v[236:239], v191 offset:32768
	ds_read_b128 v[240:243], v191 offset:45056
	s_waitcnt lgkmcnt(1)
	v_mfma_f32_32x32x16_bf16 v[82:97], v[236:239], v[142:145], v[82:97]
	s_waitcnt lgkmcnt(0)
	v_mfma_f32_32x32x16_bf16 v[66:81], v[240:243], v[142:145], v[66:81]
	s_mov_b32 m0, s26
	s_nop 0
	global_load_lds_dwordx4 v149, s[24:25]
	s_add_i32 m0, s26, 0x400
	s_nop 0
	global_load_lds_dwordx4 v150, s[24:25]
	s_add_i32 s13, s36, s37
	s_mov_b32 m0, s13
	s_nop 0
	global_load_lds_dwordx4 v146, s[24:25]
	s_add_i32 m0, s13, 0x400
	s_nop 0
	global_load_lds_dwordx4 v147, s[24:25]
	s_add_i32 m0, s13, 0x800
	s_nop 0
	global_load_lds_dwordx4 v148, s[24:25]
	s_add_u32 s24, s24, 0x40000
	s_addc_u32 s25, s25, 0
	s_xor_b32 s26, s26, 0x4000
	s_sub_i32 s37, 0x6000, s37
	s_nop 1
	v_max_f32_e32 v191, v83, v83
	v_max_f32_e32 v235, v82, v82
	v_max_f32_e32 v191, v235, v191
	v_max3_f32 v191, v191, v84, v85
	v_max3_f32 v191, v191, v86, v87
	v_max3_f32 v191, v191, v88, v89
	v_max3_f32 v191, v191, v90, v91
	v_max3_f32 v191, v191, v92, v93
	v_max3_f32 v191, v191, v94, v95
	v_max3_f32 v191, v191, v96, v97
	v_max3_f32 v191, v191, v66, v67
	v_max3_f32 v191, v191, v68, v69
	v_max3_f32 v191, v191, v70, v71
	v_max3_f32 v191, v191, v72, v73
	v_max3_f32 v191, v191, v74, v75
	v_max3_f32 v191, v191, v76, v77
	v_max3_f32 v191, v191, v78, v79
	v_max3_f32 v191, v191, v80, v81
	v_mov_b32_e32 v235, v191
	s_nop 1
	v_permlane32_swap_b32_e32 v191, v235
	v_max_f32_e32 v235, v235, v235
	v_max_f32_e32 v191, v191, v191
	v_max_f32_e32 v191, v191, v235
	v_sub_f32_e32 v235, v191, v189
	v_cmp_ge_f32_e32 vcc, s56, v235
	s_cmp_eq_u64 vcc, exec
	v_max_f32_e32 v235, v189, v189
	s_cselect_b64 vcc, -1, 0
	v_max_f32_e32 v191, v235, v191
	v_sub_f32_e32 v235, v189, v191
	v_cndmask_b32_e32 v189, v191, v189, vcc
	v_mul_f32_e32 v191, 0xbdd53b94, v189
	v_fmamk_f32 v82, v82, 0x3dd53b94, v191
	v_fmamk_f32 v83, v83, 0x3dd53b94, v191
	v_fmamk_f32 v84, v84, 0x3dd53b94, v191
	v_fmamk_f32 v85, v85, 0x3dd53b94, v191
	v_fmamk_f32 v86, v86, 0x3dd53b94, v191
	v_fmamk_f32 v87, v87, 0x3dd53b94, v191
	v_fmamk_f32 v88, v88, 0x3dd53b94, v191
	v_fmamk_f32 v89, v89, 0x3dd53b94, v191
	v_fmamk_f32 v90, v90, 0x3dd53b94, v191
	v_fmamk_f32 v91, v91, 0x3dd53b94, v191
	v_fmamk_f32 v92, v92, 0x3dd53b94, v191
	v_fmamk_f32 v93, v93, 0x3dd53b94, v191
	v_fmamk_f32 v94, v94, 0x3dd53b94, v191
	v_fmamk_f32 v95, v95, 0x3dd53b94, v191
	v_fmamk_f32 v96, v96, 0x3dd53b94, v191
	v_fmamk_f32 v97, v97, 0x3dd53b94, v191
	v_fmamk_f32 v66, v66, 0x3dd53b94, v191
	v_fmamk_f32 v67, v67, 0x3dd53b94, v191
	v_fmamk_f32 v68, v68, 0x3dd53b94, v191
	v_fmamk_f32 v69, v69, 0x3dd53b94, v191
	v_fmamk_f32 v70, v70, 0x3dd53b94, v191
	v_fmamk_f32 v71, v71, 0x3dd53b94, v191
	v_fmamk_f32 v72, v72, 0x3dd53b94, v191
	v_fmamk_f32 v73, v73, 0x3dd53b94, v191
	v_fmamk_f32 v74, v74, 0x3dd53b94, v191
	v_fmamk_f32 v75, v75, 0x3dd53b94, v191
	v_fmamk_f32 v76, v76, 0x3dd53b94, v191
	v_fmamk_f32 v77, v77, 0x3dd53b94, v191
	v_fmamk_f32 v78, v78, 0x3dd53b94, v191
	v_fmamk_f32 v79, v79, 0x3dd53b94, v191
	v_fmamk_f32 v80, v80, 0x3dd53b94, v191
	v_fmac_f32_e32 v191, 0x3dd53b94, v81
	v_exp_f32_e32 v81, v82
	v_exp_f32_e32 v236, v83
	v_exp_f32_e32 v84, v84
	v_exp_f32_e32 v85, v85
	v_exp_f32_e32 v86, v86
	v_exp_f32_e32 v237, v70
	v_add_f32_e32 v70, 0, v81
	v_exp_f32_e32 v87, v87
	v_add_f32_e32 v70, v236, v70
	v_exp_f32_e32 v88, v88
	v_add_f32_e32 v70, v84, v70
	v_exp_f32_e32 v89, v89
	v_add_f32_e32 v70, v85, v70
	v_exp_f32_e32 v90, v90
	v_add_f32_e32 v70, v86, v70
	v_exp_f32_e32 v91, v91
	v_add_f32_e32 v70, v87, v70
	v_exp_f32_e32 v92, v92
	v_add_f32_e32 v70, v88, v70
	v_exp_f32_e32 v93, v93
	v_add_f32_e32 v70, v89, v70
	v_exp_f32_e32 v94, v94
	v_add_f32_e32 v70, v90, v70
	v_exp_f32_e32 v95, v95
	v_add_f32_e32 v70, v91, v70
	v_exp_f32_e32 v96, v96
	v_add_f32_e32 v70, v92, v70
	v_exp_f32_e32 v97, v97
	v_add_f32_e32 v70, v93, v70
	v_exp_f32_e32 v66, v66
	v_add_f32_e32 v70, v94, v70
	v_exp_f32_e32 v67, v67
	v_add_f32_e32 v70, v95, v70
	v_exp_f32_e32 v68, v68
	v_add_f32_e32 v70, v96, v70
	v_exp_f32_e32 v69, v69
	v_add_f32_e32 v70, v97, v70
	v_add_f32_e32 v70, v66, v70
	v_exp_f32_e32 v238, v71
	v_add_f32_e32 v70, v67, v70
	v_exp_f32_e32 v239, v72
	v_add_f32_e32 v70, v68, v70
	v_exp_f32_e32 v73, v73
	v_add_f32_e32 v70, v69, v70
	v_exp_f32_e32 v240, v74
	v_add_f32_e32 v70, v237, v70
	v_exp_f32_e32 v241, v75
	v_add_f32_e32 v70, v238, v70
	v_exp_f32_e32 v242, v76
	v_add_f32_e32 v70, v239, v70
	v_exp_f32_e32 v243, v77
	v_add_f32_e32 v70, v73, v70
	v_exp_f32_e32 v244, v78
	v_add_f32_e32 v70, v240, v70
	v_exp_f32_e32 v245, v79
	v_add_f32_e32 v70, v241, v70
	v_exp_f32_e32 v246, v80
	v_add_f32_e32 v70, v242, v70
	v_mul_f32_e32 v235, 0x3dd53b94, v235
	v_exp_f32_e32 v191, v191
	v_add_f32_e32 v70, v243, v70
	v_exp_f32_e32 v235, v235
	v_add_f32_e32 v70, v244, v70
	v_add_f32_e32 v70, v245, v70
	v_add_f32_e32 v70, v246, v70
	v_add_f32_e32 v82, v191, v70
	v_cndmask_b32_e64 v235, v235, 1.0, vcc
	v_mov_b32_e32 v83, v82
	s_nop 1
	v_permlane32_swap_b32_e32 v82, v83
	v_cmp_gt_f32_e32 vcc, 1.0, v235
	v_cvt_pk_bf16_f32 v78, v81, v236
	v_cvt_pk_bf16_f32 v79, v84, v85
	v_cvt_pk_bf16_f32 v80, v86, v87
	v_cvt_pk_bf16_f32 v81, v88, v89
	v_cvt_pk_bf16_f32 v74, v90, v91
	v_cvt_pk_bf16_f32 v75, v92, v93
	v_cvt_pk_bf16_f32 v76, v94, v95
	v_cvt_pk_bf16_f32 v77, v96, v97
	v_cvt_pk_bf16_f32 v70, v66, v67
	v_cvt_pk_bf16_f32 v71, v68, v69
	v_cvt_pk_bf16_f32 v72, v237, v238
	v_cvt_pk_bf16_f32 v73, v239, v73
	v_cvt_pk_bf16_f32 v66, v240, v241
	v_cvt_pk_bf16_f32 v67, v242, v243
	v_cvt_pk_bf16_f32 v68, v244, v245
	v_cvt_pk_bf16_f32 v69, v246, v191
	s_cbranch_vccz .LBB0_124
	s_and_saveexec_b64 s[12:13], s[4:5]
	ds_write_b32 v232, v235 offset:128
	s_or_b64 exec, exec, s[12:13]
	s_waitcnt lgkmcnt(0)
	v_add_u32_e32 v96, v196, v202
	ds_read_b128 v[84:87], v96 offset:224
	ds_read_b128 v[88:91], v96 offset:192
	ds_read_b128 v[92:95], v96 offset:160
	ds_read_b128 v[236:239], v96 offset:128
	s_waitcnt lgkmcnt(3)
	v_pk_mul_f32 v[14:15], v[14:15], v[84:85]
	s_waitcnt lgkmcnt(2)
	v_pk_mul_f32 v[10:11], v[10:11], v[88:89]
	s_waitcnt lgkmcnt(1)
	v_pk_mul_f32 v[6:7], v[6:7], v[92:93]
	v_pk_mul_f32 v[16:17], v[16:17], v[86:87]
	v_pk_mul_f32 v[12:13], v[12:13], v[90:91]
	v_pk_mul_f32 v[8:9], v[8:9], v[94:95]
	s_waitcnt lgkmcnt(0)
	v_pk_mul_f32 v[4:5], v[4:5], v[238:239]
	v_pk_mul_f32 v[2:3], v[2:3], v[236:237]
	v_pk_mul_f32 v[30:31], v[30:31], v[84:85]
	v_pk_mul_f32 v[26:27], v[26:27], v[88:89]
	v_pk_mul_f32 v[22:23], v[22:23], v[92:93]
	v_pk_mul_f32 v[32:33], v[32:33], v[86:87]
	v_pk_mul_f32 v[28:29], v[28:29], v[90:91]
	v_pk_mul_f32 v[24:25], v[24:25], v[94:95]
	v_pk_mul_f32 v[20:21], v[20:21], v[238:239]
	v_pk_mul_f32 v[18:19], v[18:19], v[236:237]
	v_pk_mul_f32 v[46:47], v[46:47], v[84:85]
	v_pk_mul_f32 v[42:43], v[42:43], v[88:89]
	v_pk_mul_f32 v[38:39], v[38:39], v[92:93]
	v_pk_mul_f32 v[48:49], v[48:49], v[86:87]
	v_pk_mul_f32 v[44:45], v[44:45], v[90:91]
	v_pk_mul_f32 v[40:41], v[40:41], v[94:95]
	v_pk_mul_f32 v[36:37], v[36:37], v[238:239]
	v_pk_mul_f32 v[34:35], v[34:35], v[236:237]
	v_pk_mul_f32 v[62:63], v[62:63], v[84:85]
	v_pk_mul_f32 v[58:59], v[58:59], v[88:89]
	v_pk_mul_f32 v[54:55], v[54:55], v[92:93]
	v_pk_mul_f32 v[64:65], v[64:65], v[86:87]
	v_pk_mul_f32 v[60:61], v[60:61], v[90:91]
	v_pk_mul_f32 v[56:57], v[56:57], v[94:95]
	v_pk_mul_f32 v[52:53], v[52:53], v[238:239]
	v_pk_mul_f32 v[50:51], v[50:51], v[236:237]
.LBB0_124:
	v_add_f32_e32 v191, v82, v83
	v_fmac_f32_e32 v191, v234, v235
	v_lshl_add_u32 v234, s23, 14, v233
	ds_read_b64_tr_b16 v[82:83], v234 offset:0
	ds_read_b64_tr_b16 v[84:85], v234 offset:0x800
	ds_read_b64_tr_b16 v[86:87], v234 offset:0x1000
	ds_read_b64_tr_b16 v[88:89], v234 offset:0x1800
	ds_read_b64_tr_b16 v[90:91], v234 offset:0x2000
	ds_read_b64_tr_b16 v[92:93], v234 offset:0x2800
	ds_read_b64_tr_b16 v[94:95], v234 offset:0x3000
	ds_read_b64_tr_b16 v[96:97], v234 offset:0x3800
	s_waitcnt lgkmcnt(0)
	s_nop 0
	v_mfma_f32_32x32x16_bf16 v[2:17], v[78:81], v[82:85], v[2:17]
	ds_read_b64_tr_b16 v[82:83], v234 offset:0x200
	ds_read_b64_tr_b16 v[84:85], v234 offset:0xa00
	v_mfma_f32_32x32x16_bf16 v[2:17], v[74:77], v[86:89], v[2:17]
	ds_read_b64_tr_b16 v[86:87], v234 offset:0x1200
	ds_read_b64_tr_b16 v[88:89], v234 offset:0x1a00
	v_mfma_f32_32x32x16_bf16 v[2:17], v[70:73], v[90:93], v[2:17]
	ds_read_b64_tr_b16 v[90:91], v234 offset:0x2200
	ds_read_b64_tr_b16 v[92:93], v234 offset:0x2a00
	v_mfma_f32_32x32x16_bf16 v[2:17], v[66:69], v[94:97], v[2:17]
	ds_read_b64_tr_b16 v[94:95], v234 offset:0x3200
	ds_read_b64_tr_b16 v[96:97], v234 offset:0x3a00
	s_waitcnt lgkmcnt(0)
	v_mfma_f32_32x32x16_bf16 v[18:33], v[78:81], v[82:85], v[18:33]
	ds_read_b64_tr_b16 v[82:83], v234 offset:0x400
	ds_read_b64_tr_b16 v[84:85], v234 offset:0xc00
	v_mfma_f32_32x32x16_bf16 v[18:33], v[74:77], v[86:89], v[18:33]
	ds_read_b64_tr_b16 v[86:87], v234 offset:0x1400
	ds_read_b64_tr_b16 v[88:89], v234 offset:0x1c00
	v_mfma_f32_32x32x16_bf16 v[18:33], v[70:73], v[90:93], v[18:33]
	ds_read_b64_tr_b16 v[90:91], v234 offset:0x2400
	ds_read_b64_tr_b16 v[92:93], v234 offset:0x2c00
	v_mfma_f32_32x32x16_bf16 v[18:33], v[66:69], v[94:97], v[18:33]
	ds_read_b64_tr_b16 v[94:95], v234 offset:0x3400
	ds_read_b64_tr_b16 v[96:97], v234 offset:0x3c00
	s_waitcnt lgkmcnt(0)
	v_mfma_f32_32x32x16_bf16 v[34:49], v[78:81], v[82:85], v[34:49]
	ds_read_b64_tr_b16 v[82:83], v234 offset:0x600
	ds_read_b64_tr_b16 v[84:85], v234 offset:0xe00
	v_mfma_f32_32x32x16_bf16 v[34:49], v[74:77], v[86:89], v[34:49]
	ds_read_b64_tr_b16 v[86:87], v234 offset:0x1600
	ds_read_b64_tr_b16 v[88:89], v234 offset:0x1e00
	v_mfma_f32_32x32x16_bf16 v[34:49], v[70:73], v[90:93], v[34:49]
	ds_read_b64_tr_b16 v[90:91], v234 offset:0x2600
	ds_read_b64_tr_b16 v[92:93], v234 offset:0x2e00
	v_mfma_f32_32x32x16_bf16 v[34:49], v[66:69], v[94:97], v[34:49]
	ds_read_b64_tr_b16 v[94:95], v234 offset:0x3600
	ds_read_b64_tr_b16 v[96:97], v234 offset:0x3e00
	s_waitcnt lgkmcnt(0)
	v_mfma_f32_32x32x16_bf16 v[50:65], v[78:81], v[82:85], v[50:65]
	s_xor_b32 s12, s23, 1
	s_lshl_b32 s13, s12, 14
	s_add_i32 s13, s13, 16
	s_lshl_b32 s12, s12, 13
	s_add_i32 s13, s13, s12
	v_mfma_f32_32x32x16_bf16 v[50:65], v[74:77], v[86:89], v[50:65]
	s_add_u32 s10, s10, 0x40000
	s_addc_u32 s11, s11, 0
	s_add_i32 s22, s22, 1
	s_cmp_eq_u32 s21, s10
	v_mfma_f32_32x32x16_bf16 v[50:65], v[70:73], v[90:93], v[50:65]
	s_waitcnt vmcnt(0)
	s_barrier
	v_mfma_f32_32x32x16_bf16 v[50:65], v[66:69], v[94:97], v[50:65]
	s_cbranch_scc1 .LBB0_126
	v_mov_b32_e32 v234, v191
	s_branch .LBB0_120

.LBB0_286:
	s_and_b32 s11, s15, 0x4000
	v_add_u32_e32 v90, s11, v227
	v_add_u32_e32 v86, v90, v228
	ds_read_b128 v[82:85], v86 offset:32768
	ds_read_b128 v[86:89], v86 offset:40960
	s_waitcnt lgkmcnt(1)
	v_mfma_f32_32x32x16_bf16 v[114:129], v[82:85], v[134:137], v[66:81]
	s_waitcnt lgkmcnt(0)
	v_mfma_f32_32x32x16_bf16 v[98:113], v[86:89], v[134:137], v[66:81]
	v_add_u32_e32 v86, v90, v229
	ds_read_b128 v[82:85], v86 offset:32768
	ds_read_b128 v[86:89], v86 offset:40960
	s_waitcnt lgkmcnt(1)
	v_mfma_f32_32x32x16_bf16 v[114:129], v[82:85], v[142:145], v[114:129]
	s_waitcnt lgkmcnt(0)
	v_mfma_f32_32x32x16_bf16 v[98:113], v[86:89], v[142:145], v[98:113]
	v_add_u32_e32 v86, v90, v230
	ds_read_b128 v[82:85], v86 offset:32768
	ds_read_b128 v[86:89], v86 offset:40960
	s_waitcnt lgkmcnt(1)
	v_mfma_f32_32x32x16_bf16 v[114:129], v[82:85], v[146:149], v[114:129]
	s_waitcnt lgkmcnt(0)
	v_mfma_f32_32x32x16_bf16 v[98:113], v[86:89], v[146:149], v[98:113]
	v_add_u32_e32 v86, v90, v231
	ds_read_b128 v[82:85], v86 offset:32768
	ds_read_b128 v[86:89], v86 offset:40960
	s_waitcnt lgkmcnt(1)
	v_mfma_f32_32x32x16_bf16 v[114:129], v[82:85], v[150:153], v[114:129]
	s_waitcnt lgkmcnt(0)
	v_mfma_f32_32x32x16_bf16 v[98:113], v[86:89], v[150:153], v[98:113]
	v_add_u32_e32 v86, v90, v232
	ds_read_b128 v[82:85], v86 offset:32768
	ds_read_b128 v[86:89], v86 offset:40960
	s_waitcnt lgkmcnt(1)
	v_mfma_f32_32x32x16_bf16 v[114:129], v[82:85], v[154:157], v[114:129]
	s_waitcnt lgkmcnt(0)
	v_mfma_f32_32x32x16_bf16 v[98:113], v[86:89], v[154:157], v[98:113]
	v_add_u32_e32 v86, v90, v233
	ds_read_b128 v[82:85], v86 offset:32768
	ds_read_b128 v[86:89], v86 offset:40960
	s_waitcnt lgkmcnt(1)
	v_mfma_f32_32x32x16_bf16 v[114:129], v[82:85], v[158:161], v[114:129]
	s_waitcnt lgkmcnt(0)
	v_mfma_f32_32x32x16_bf16 v[98:113], v[86:89], v[158:161], v[98:113]
	v_add_u32_e32 v86, v90, v234
	ds_read_b128 v[82:85], v86 offset:32768
	ds_read_b128 v[86:89], v86 offset:40960
	s_waitcnt lgkmcnt(1)
	v_mfma_f32_32x32x16_bf16 v[114:129], v[82:85], v[138:141], v[114:129]
	s_waitcnt lgkmcnt(0)
	v_mfma_f32_32x32x16_bf16 v[98:113], v[86:89], v[138:141], v[98:113]
	v_add_u32_e32 v86, v90, v235
	ds_read_b128 v[82:85], v86 offset:32768
	ds_read_b128 v[86:89], v86 offset:40960
	s_waitcnt lgkmcnt(1)
	v_mfma_f32_32x32x16_bf16 v[114:129], v[82:85], v[130:133], v[114:129]
	s_waitcnt lgkmcnt(0)
	v_mfma_f32_32x32x16_bf16 v[98:113], v[86:89], v[130:133], v[98:113]
	s_mov_b32 m0, s26
	s_nop 0
	global_load_lds_dwordx4 v250, s[24:25]
	s_add_i32 m0, s26, 0x400
	s_nop 0
	global_load_lds_dwordx4 v251, s[24:25]
	s_add_i32 m0, s26, 0x8000
	s_nop 0
	global_load_lds_dwordx4 v252, s[24:25]
	s_add_i32 m0, s26, 0x8400
	s_nop 0
	global_load_lds_dwordx4 v253, s[24:25]
	s_add_u32 s24, s24, 0x50000
	s_addc_u32 s25, s25, 0
	s_nop 1
	v_max_f32_e32 v82, v115, v115
	v_max_f32_e32 v83, v114, v114
	v_max_f32_e32 v82, v83, v82
	v_max3_f32 v82, v82, v116, v117
	v_max3_f32 v82, v82, v118, v119
	v_max3_f32 v82, v82, v120, v121
	v_max3_f32 v82, v82, v122, v123
	v_max3_f32 v82, v82, v124, v125
	v_max3_f32 v82, v82, v126, v127
	v_max3_f32 v82, v82, v128, v129
	v_max3_f32 v82, v82, v98, v99
	v_max3_f32 v82, v82, v100, v101
	v_max3_f32 v82, v82, v102, v103
	v_max3_f32 v82, v82, v104, v105
	v_max3_f32 v82, v82, v106, v107
	v_max3_f32 v82, v82, v108, v109
	v_max3_f32 v82, v82, v110, v111
	v_max3_f32 v82, v82, v112, v113
	v_mov_b32_e32 v83, v82
	s_nop 1
	v_permlane32_swap_b32_e32 v82, v83
	v_max_f32_e32 v83, v83, v83
	v_max_f32_e32 v82, v82, v82
	v_max_f32_e32 v82, v82, v83
	v_cmp_ge_f32_e32 vcc, s64, v82
	s_cmp_eq_u64 vcc, exec
	s_cbranch_scc0 .LBB0_294
	v_mov_b32_e32 v195, 1.0

.LBB0_295:
	v_mov_b64_e32 v[82:83], v[66:67]
	v_mov_b64_e32 v[84:85], v[68:69]
	v_mov_b64_e32 v[86:87], v[70:71]
	v_mov_b64_e32 v[88:89], v[72:73]
	v_mov_b64_e32 v[90:91], v[74:75]
	v_mov_b64_e32 v[92:93], v[76:77]
	v_mov_b64_e32 v[94:95], v[78:79]
	v_mov_b64_e32 v[96:97], v[80:81]
	s_lshl_b32 s10, s14, 14
	s_addk_i32 s10, 0x4000
	s_and_b32 s12, s10, 0x4000
	v_add_u32_e32 v102, s12, v227
	v_add_u32_e32 v103, v102, v228
	ds_read_b128 v[98:101], v103 offset:32768
	s_waitcnt lgkmcnt(0)
	v_mfma_f32_32x32x16_bf16 v[66:81], v[98:101], v[134:137], v[82:97]
	ds_read_b128 v[98:101], v103 offset:40960
	v_add_u32_e32 v103, v102, v229
	s_waitcnt lgkmcnt(0)
	v_mfma_f32_32x32x16_bf16 v[82:97], v[98:101], v[134:137], v[82:97]
	ds_read_b128 v[98:101], v103 offset:32768
	s_waitcnt lgkmcnt(0)
	v_mfma_f32_32x32x16_bf16 v[66:81], v[98:101], v[142:145], v[66:81]
	ds_read_b128 v[98:101], v103 offset:40960
	v_add_u32_e32 v103, v102, v230
	s_waitcnt lgkmcnt(0)
	v_mfma_f32_32x32x16_bf16 v[82:97], v[98:101], v[142:145], v[82:97]
	ds_read_b128 v[98:101], v103 offset:32768
	s_waitcnt lgkmcnt(0)
	v_mfma_f32_32x32x16_bf16 v[66:81], v[98:101], v[146:149], v[66:81]
	ds_read_b128 v[98:101], v103 offset:40960
	v_add_u32_e32 v103, v102, v231
	s_waitcnt lgkmcnt(0)
	v_mfma_f32_32x32x16_bf16 v[82:97], v[98:101], v[146:149], v[82:97]
	ds_read_b128 v[98:101], v103 offset:32768
	s_waitcnt lgkmcnt(0)
	v_mfma_f32_32x32x16_bf16 v[66:81], v[98:101], v[150:153], v[66:81]
	ds_read_b128 v[98:101], v103 offset:40960
	v_add_u32_e32 v103, v102, v232
	s_waitcnt lgkmcnt(0)
	v_mfma_f32_32x32x16_bf16 v[82:97], v[98:101], v[150:153], v[82:97]
	ds_read_b128 v[98:101], v103 offset:32768
	s_waitcnt lgkmcnt(0)
	v_mfma_f32_32x32x16_bf16 v[66:81], v[98:101], v[154:157], v[66:81]
	ds_read_b128 v[98:101], v103 offset:40960
	v_add_u32_e32 v103, v102, v233
	s_waitcnt lgkmcnt(0)
	v_mfma_f32_32x32x16_bf16 v[82:97], v[98:101], v[154:157], v[82:97]
	ds_read_b128 v[98:101], v103 offset:32768
	s_waitcnt lgkmcnt(0)
	v_mfma_f32_32x32x16_bf16 v[66:81], v[98:101], v[158:161], v[66:81]
	ds_read_b128 v[98:101], v103 offset:40960
	v_add_u32_e32 v103, v102, v234
	v_add_u32_e32 v102, v102, v235
	s_waitcnt lgkmcnt(0)
	v_mfma_f32_32x32x16_bf16 v[82:97], v[98:101], v[158:161], v[82:97]
	ds_read_b128 v[98:101], v103 offset:32768
	s_waitcnt lgkmcnt(0)
	v_mfma_f32_32x32x16_bf16 v[66:81], v[98:101], v[138:141], v[66:81]
	ds_read_b128 v[98:101], v102 offset:32768
	s_waitcnt lgkmcnt(0)
	v_mfma_f32_32x32x16_bf16 v[66:81], v[98:101], v[130:133], v[66:81]
	ds_read_b128 v[98:101], v103 offset:40960
	ds_read_b128 v[102:105], v102 offset:40960
	s_waitcnt lgkmcnt(1)
	v_mfma_f32_32x32x16_bf16 v[82:97], v[98:101], v[138:141], v[82:97]
	s_nop 7
	v_max_f32_e32 v106, v67, v67
	v_max_f32_e32 v107, v66, v66
	v_max_f32_e32 v106, v107, v106
	v_max3_f32 v98, v106, v68, v69
	v_max3_f32 v98, v98, v70, v71
	v_max3_f32 v98, v98, v72, v73
	v_max3_f32 v98, v98, v74, v75
	s_waitcnt lgkmcnt(0)
	v_mfma_f32_32x32x16_bf16 v[82:97], v[102:105], v[130:133], v[82:97]
	v_max3_f32 v98, v98, v76, v77
	v_max3_f32 v98, v98, v78, v79
	v_max3_f32 v98, v98, v80, v81
	s_nop 8
	v_max3_f32 v98, v98, v82, v83
	v_max3_f32 v98, v98, v84, v85
	v_max3_f32 v98, v98, v86, v87
	v_max3_f32 v98, v98, v88, v89
	v_max3_f32 v98, v98, v90, v91
	v_max3_f32 v98, v98, v92, v93
	v_max3_f32 v98, v98, v94, v95
	v_max3_f32 v98, v98, v96, v97
	v_mov_b32_e32 v99, v98
	s_nop 1
	v_permlane32_swap_b32_e32 v98, v99
	v_max_f32_e32 v99, v99, v99
	v_max_f32_e32 v98, v98, v98
	v_max_f32_e32 v99, v98, v99
	v_cmp_ge_f32_e32 vcc, s64, v99
	s_cmp_eq_u64 vcc, exec
	v_mov_b32_e32 v98, 1.0
	s_cbranch_scc0 .LBB0_307

.LBB0_575:
	s_cmp_eq_u32 s47, 23
	s_cbranch_scc1 .LBB0_632
	s_getreg_b32 s2, hwreg(HW_REG_XCC_ID, 0, 4)
	s_waitcnt vmcnt(0)
	v_cmp_eq_u32_e32 vcc, 0, v178
	s_waitcnt vmcnt(0) lgkmcnt(0)
	s_barrier
	s_and_saveexec_b64 s[0:1], vcc
	s_cbranch_execz .LBB0_630
	s_waitcnt vmcnt(0) expcnt(0) lgkmcnt(0)
	ds_read_b32 v3, v1
	ds_read_b32 v0, v1 offset:4
	s_and_b32 s2, s2, 15
	s_waitcnt lgkmcnt(1)
	v_cmp_ne_u32_e32 vcc, 0, v3
	s_cbranch_vccnz .LBB0_592
	s_add_u32 s4, s98, 0x1d588200
	s_addc_u32 s5, s99, 0
	s_add_u32 s6, s98, 0x1d588400
	s_addc_u32 s7, s99, 0
	s_add_u32 s8, s98, 0x1d588500
	s_addc_u32 s9, s99, 0
	s_add_u32 s10, s98, 0x1d588600
	s_addc_u32 s11, s99, 0
	s_add_u32 s12, s98, 0x1d588700
	s_addc_u32 s13, s99, 0
	s_add_u32 s14, s98, 0x1d588800
	s_addc_u32 s15, s99, 0
	s_add_u32 s16, s98, 0x1d588900
	s_addc_u32 s17, s99, 0
	s_add_u32 s18, s98, 0x1d588a00
	s_addc_u32 s19, s99, 0
	s_add_u32 s20, s98, 0x1d588b00
	s_addc_u32 s21, s99, 0
	s_add_u32 s22, s98, 0x1d588c00
	s_addc_u32 s23, s99, 0
	s_add_u32 s24, s98, 0x1d588d00
	s_addc_u32 s25, s99, 0
	s_add_u32 s26, s98, 0x1d588e00
	s_addc_u32 s27, s99, 0
	s_add_u32 s28, s98, 0x1d588f00
	s_addc_u32 s29, s99, 0
	s_add_u32 s30, s98, 0x1d589000
	s_addc_u32 s31, s99, 0
	s_add_u32 s34, s98, 0x1d589100
	s_addc_u32 s35, s99, 0
	s_add_u32 s36, s98, 0x1d589200
	s_addc_u32 s37, s99, 0
	s_add_u32 s38, s98, 0x1d589300
	s_addc_u32 s39, s99, 0
	s_mov_b32 s50, 1
	s_branch .LBB0_579
